# prep: pipeline c1/c2 and bias k-loops (8 iterations of loads in flight, same summation order)
# speedup vs baseline: 1.0059x; 1.0037x over previous
; DI bf16_t f2bf(float a) { return (bf16_t)(pack2(a, 0.f) & 0xffffu); }
; DI float bf2f(bf16_t b) { return __uint_as_float(((unsigned)b) << 16); }
; DI void phase_prep(const Params& P, unsigned char* smem, int L, int G) {
;     ...
;     for (int t = L; t < 128; t += G) {
;       const int i = t >> 5, n0 = (t & 31) * 32;
;       const int kp = tid >> 5, nn = tid & 31;
;       const float* W = P.pe_gate + (size_t)i * 1024 * 1024;
;       const float* g = P.ln_g + i * 1024; const float* bb = P.ln_b + i * 1024;
;       float s1 = 0.f, s2 = 0.f;
;       for (int k = kp * 64; k < kp * 64 + 64; ++k) {
;         const float wv = W[(size_t)k * 1024 + n0 + nn];
;         s1 += bf2f(f2bf(g[k] * wv)); s2 += bb[k] * wv;
;       }
;       __syncthreads();
;       red[kp * 32 + nn] = s1; red[512 + kp * 32 + nn] = s2;
;       __syncthreads();
;       if (tid < 32) {
;         float a = 0.f, b2 = 0.f;
;         for (int q = 0; q < 16; ++q) { a += red[q * 32 + tid]; b2 += red[512 + q * 32 + tid]; }
;         c1[i * 1024 + n0 + tid] = a; c2[i * 1024 + n0 + tid] = b2;
;       }
;     }
.LBB0_157:
	s_mov_b32 s98, 8
.Lmy_c12_loop:
	global_load_dword v40, v[14:15], off
	global_load_dword v41, v[10:11], off offset:0
	global_load_dword v43, v[12:13], off offset:0
	v_lshl_add_u64 v[14:15], v[14:15], 0, s[2:3]
	global_load_dword v44, v[14:15], off
	global_load_dword v45, v[10:11], off offset:4
	global_load_dword v47, v[12:13], off offset:4
	v_lshl_add_u64 v[14:15], v[14:15], 0, s[2:3]
	global_load_dword v48, v[14:15], off
	global_load_dword v49, v[10:11], off offset:8
	global_load_dword v51, v[12:13], off offset:8
	v_lshl_add_u64 v[14:15], v[14:15], 0, s[2:3]
	global_load_dword v52, v[14:15], off
	global_load_dword v53, v[10:11], off offset:12
	global_load_dword v55, v[12:13], off offset:12
	v_lshl_add_u64 v[14:15], v[14:15], 0, s[2:3]
	global_load_dword v56, v[14:15], off
	global_load_dword v57, v[10:11], off offset:16
	global_load_dword v59, v[12:13], off offset:16
	v_lshl_add_u64 v[14:15], v[14:15], 0, s[2:3]
	global_load_dword v60, v[14:15], off
	global_load_dword v61, v[10:11], off offset:20
	global_load_dword v63, v[12:13], off offset:20
	v_lshl_add_u64 v[14:15], v[14:15], 0, s[2:3]
	global_load_dword v64, v[14:15], off
	global_load_dword v65, v[10:11], off offset:24
	global_load_dword v67, v[12:13], off offset:24
	v_lshl_add_u64 v[14:15], v[14:15], 0, s[2:3]
	global_load_dword v68, v[14:15], off
	global_load_dword v69, v[10:11], off offset:28
	global_load_dword v71, v[12:13], off offset:28
	v_lshl_add_u64 v[14:15], v[14:15], 0, s[2:3]
	v_lshl_add_u64 v[10:11], v[10:11], 0, 32
	v_lshl_add_u64 v[12:13], v[12:13], 0, 32
	s_waitcnt vmcnt(21)
	v_mul_f32_e32 v41, v40, v41
	v_mul_f32_e32 v43, v40, v43
	v_cvt_pk_bf16_f32 v41, v41, s0
	v_lshlrev_b32_e32 v42, 16, v41
	v_pk_add_f32 v[8:9], v[8:9], v[42:43]
	s_waitcnt vmcnt(18)
	v_mul_f32_e32 v45, v44, v45
	v_mul_f32_e32 v47, v44, v47
	v_cvt_pk_bf16_f32 v45, v45, s0
	v_lshlrev_b32_e32 v46, 16, v45
	v_pk_add_f32 v[8:9], v[8:9], v[46:47]
	s_waitcnt vmcnt(15)
	v_mul_f32_e32 v49, v48, v49
	v_mul_f32_e32 v51, v48, v51
	v_cvt_pk_bf16_f32 v49, v49, s0
	v_lshlrev_b32_e32 v50, 16, v49
	v_pk_add_f32 v[8:9], v[8:9], v[50:51]
	s_waitcnt vmcnt(12)
	v_mul_f32_e32 v53, v52, v53
	v_mul_f32_e32 v55, v52, v55
	v_cvt_pk_bf16_f32 v53, v53, s0
	v_lshlrev_b32_e32 v54, 16, v53
	v_pk_add_f32 v[8:9], v[8:9], v[54:55]
	s_waitcnt vmcnt(9)
	v_mul_f32_e32 v57, v56, v57
	v_mul_f32_e32 v59, v56, v59
	v_cvt_pk_bf16_f32 v57, v57, s0
	v_lshlrev_b32_e32 v58, 16, v57
	v_pk_add_f32 v[8:9], v[8:9], v[58:59]
	s_waitcnt vmcnt(6)
	v_mul_f32_e32 v61, v60, v61
	v_mul_f32_e32 v63, v60, v63
	v_cvt_pk_bf16_f32 v61, v61, s0
	v_lshlrev_b32_e32 v62, 16, v61
	v_pk_add_f32 v[8:9], v[8:9], v[62:63]
	s_waitcnt vmcnt(3)
	v_mul_f32_e32 v65, v64, v65
	v_mul_f32_e32 v67, v64, v67
	v_cvt_pk_bf16_f32 v65, v65, s0
	v_lshlrev_b32_e32 v66, 16, v65
	v_pk_add_f32 v[8:9], v[8:9], v[66:67]
	s_waitcnt vmcnt(0)
	v_mul_f32_e32 v69, v68, v69
	v_mul_f32_e32 v71, v68, v71
	v_cvt_pk_bf16_f32 v69, v69, s0
	v_lshlrev_b32_e32 v70, 16, v69
	v_pk_add_f32 v[8:9], v[8:9], v[70:71]
	s_sub_u32 s98, s98, 1
	s_cmp_lg_u32 s98, 0
	s_cbranch_scc1 .Lmy_c12_loop
	s_or_b64 exec, exec, s[6:7]
	s_barrier
	ds_write_b32 v1, v8
	ds_write_b32 v16, v9 offset:2048
	s_waitcnt lgkmcnt(0)
	s_barrier
	s_and_saveexec_b64 s[6:7], s[0:1]
	s_cbranch_execz .LBB0_155
	ds_read2_b32 v[8:9], v1 offset1:32
	ds_read2_b32 v[10:11], v19 offset1:32
	ds_read2_b32 v[12:13], v1 offset0:64 offset1:96
	ds_read2_b32 v[14:15], v19 offset0:64 offset1:96
	s_lshl_b32 s5, s35, 5
	s_waitcnt lgkmcnt(3)
	v_add_f32_e32 v8, 0, v8
	v_add_f32_e32 v8, v8, v9
	s_waitcnt lgkmcnt(1)
	v_add_f32_e32 v12, v8, v12
	ds_read2_b32 v[8:9], v1 offset0:128 offset1:160
	v_add_f32_e32 v10, 0, v10
	v_add_f32_e32 v10, v10, v11
	s_waitcnt lgkmcnt(1)
	v_add_f32_e32 v14, v10, v14
	ds_read2_b32 v[10:11], v19 offset0:128 offset1:160
	v_add_f32_e32 v12, v12, v13
	s_waitcnt lgkmcnt(1)
	v_add_f32_e32 v8, v12, v8
	ds_read2_b32 v[12:13], v1 offset0:192 offset1:224
	v_add_f32_e32 v14, v14, v15
	s_waitcnt lgkmcnt(1)
	v_add_f32_e32 v10, v14, v10
	ds_read2_b32 v[14:15], v19 offset0:192 offset1:224
	v_add_f32_e32 v8, v8, v9
	s_waitcnt lgkmcnt(1)
	v_add_f32_e32 v12, v8, v12
	ds_read2_b32 v[8:9], v20 offset1:32
	v_add_f32_e32 v10, v10, v11
	s_waitcnt lgkmcnt(1)
	v_add_f32_e32 v14, v10, v14
	ds_read2_b32 v[10:11], v21 offset1:32
	v_add_f32_e32 v12, v12, v13
	s_waitcnt lgkmcnt(1)
	v_add_f32_e32 v8, v12, v8
	ds_read2_b32 v[12:13], v20 offset0:64 offset1:96
	v_add_f32_e32 v14, v14, v15
	s_waitcnt lgkmcnt(1)
	v_add_f32_e32 v10, v14, v10
	ds_read2_b32 v[14:15], v21 offset0:64 offset1:96
	v_add_f32_e32 v8, v8, v9
	v_add_f32_e32 v10, v10, v11
	s_waitcnt lgkmcnt(1)
	v_add_f32_e32 v11, v8, v12
	ds_read2_b32 v[8:9], v20 offset0:128 offset1:160
	s_waitcnt lgkmcnt(1)
	v_add_f32_e32 v12, v10, v14
	v_add_f32_e32 v13, v11, v13
	ds_read2_b32 v[10:11], v21 offset0:128 offset1:160
	v_add_f32_e32 v22, v12, v15
	s_waitcnt lgkmcnt(1)
	v_add_f32_e32 v8, v13, v8
	ds_read2_b32 v[12:13], v20 offset0:192 offset1:224
	ds_read2_b32 v[14:15], v21 offset0:192 offset1:224
	s_and_b32 s5, s5, 0x3e0
	s_waitcnt lgkmcnt(2)
	v_add_f32_e32 v10, v22, v10
	v_add_f32_e32 v8, v8, v9
	v_add_f32_e32 v9, v10, v11
	s_waitcnt lgkmcnt(1)
	v_add_f32_e32 v8, v8, v12
	s_add_i32 s4, s4, s5
	s_waitcnt lgkmcnt(0)
	v_add_f32_e32 v9, v9, v14
	v_add_f32_e32 v12, v8, v13
	v_add_u32_e32 v8, s4, v0
	v_add_f32_e32 v13, v9, v15
	v_ashrrev_i32_e32 v9, 31, v8
	v_lshlrev_b64 v[8:9], 2, v[8:9]
	v_lshl_add_u64 v[10:11], s[10:11], 0, v[8:9]
	v_lshl_add_u64 v[8:9], s[20:21], 0, v[8:9]
	global_store_dword v[10:11], v12, off
	global_store_dword v[8:9], v13, off
	s_branch .LBB0_155

; DI void phase_prep(const Params& P, unsigned char* smem, int L, int G) {
;     ...
;     for (int t = L; t < 16; t += G) {
;       const int which = t >> 3, n0 = (t & 7) * 32;
;       const int kp = tid >> 5, nn = tid & 31;
;       const float* W = which ? P.l2_phi_v1 : P.l2_phi_k1;
;       float s1 = 0.f;
;       for (int k = kp * 128; k < kp * 128 + 128; ++k) s1 += P.l2_cmp_pos[k] * W[(size_t)k * 256 + n0 + nn];
;       __syncthreads();
;       red[kp * 32 + nn] = s1;
;       __syncthreads();
;       if (tid < 32) { float a = 0.f; for (int q = 0; q < 16; ++q) a += red[q * 32 + tid]; bias[which * 256 + n0 + tid] = a; }
;     }
.LBB0_164:
	s_mov_b32 s98, 16
.Lmy_bias_loop:
	global_load_dword v40, v[8:9], off offset:0
	global_load_dword v41, v[6:7], off
	v_lshl_add_u64 v[6:7], v[6:7], 0, s[4:5]
	global_load_dword v42, v[8:9], off offset:4
	global_load_dword v43, v[6:7], off
	v_lshl_add_u64 v[6:7], v[6:7], 0, s[4:5]
	global_load_dword v44, v[8:9], off offset:8
	global_load_dword v45, v[6:7], off
	v_lshl_add_u64 v[6:7], v[6:7], 0, s[4:5]
	global_load_dword v46, v[8:9], off offset:12
	global_load_dword v47, v[6:7], off
	v_lshl_add_u64 v[6:7], v[6:7], 0, s[4:5]
	global_load_dword v48, v[8:9], off offset:16
	global_load_dword v49, v[6:7], off
	v_lshl_add_u64 v[6:7], v[6:7], 0, s[4:5]
	global_load_dword v50, v[8:9], off offset:20
	global_load_dword v51, v[6:7], off
	v_lshl_add_u64 v[6:7], v[6:7], 0, s[4:5]
	global_load_dword v52, v[8:9], off offset:24
	global_load_dword v53, v[6:7], off
	v_lshl_add_u64 v[6:7], v[6:7], 0, s[4:5]
	global_load_dword v54, v[8:9], off offset:28
	global_load_dword v55, v[6:7], off
	v_lshl_add_u64 v[6:7], v[6:7], 0, s[4:5]
	v_lshl_add_u64 v[8:9], v[8:9], 0, 32
	s_waitcnt vmcnt(14)
	v_fmac_f32_e32 v13, v40, v41
	s_waitcnt vmcnt(12)
	v_fmac_f32_e32 v13, v42, v43
	s_waitcnt vmcnt(10)
	v_fmac_f32_e32 v13, v44, v45
	s_waitcnt vmcnt(8)
	v_fmac_f32_e32 v13, v46, v47
	s_waitcnt vmcnt(6)
	v_fmac_f32_e32 v13, v48, v49
	s_waitcnt vmcnt(4)
	v_fmac_f32_e32 v13, v50, v51
	s_waitcnt vmcnt(2)
	v_fmac_f32_e32 v13, v52, v53
	s_waitcnt vmcnt(0)
	v_fmac_f32_e32 v13, v54, v55
	s_sub_u32 s98, s98, 1
	s_cmp_lg_u32 s98, 0
	s_cbranch_scc1 .Lmy_bias_loop
	s_or_b64 exec, exec, s[30:31]
	s_barrier
	ds_write_b32 v1, v13
	s_waitcnt lgkmcnt(0)
	s_barrier
	s_and_saveexec_b64 s[0:1], vcc
	s_cbranch_execz .LBB0_162
	ds_read2_b32 v[6:7], v1 offset1:32
	ds_read2_b32 v[8:9], v1 offset0:64 offset1:96
	ds_read2_b32 v[14:15], v1 offset0:128 offset1:160
	ds_read2_b32 v[16:17], v1 offset0:192 offset1:224
	ds_read2_b32 v[18:19], v12 offset1:32
	s_waitcnt lgkmcnt(4)
	v_add_f32_e32 v6, 0, v6
	v_add_f32_e32 v6, v6, v7
	s_waitcnt lgkmcnt(3)
	v_add_f32_e32 v6, v6, v8
	v_add_f32_e32 v6, v6, v9
	s_waitcnt lgkmcnt(2)
	v_add_f32_e32 v6, v6, v14
	v_add_f32_e32 v6, v6, v15
	s_waitcnt lgkmcnt(1)
	v_add_f32_e32 v6, v6, v16
	v_add_f32_e32 v8, v6, v17
	ds_read2_b32 v[6:7], v12 offset0:64 offset1:96
	s_waitcnt lgkmcnt(1)
	v_add_f32_e32 v13, v8, v18
	ds_read2_b32 v[8:9], v12 offset0:128 offset1:160
	v_add_f32_e32 v13, v13, v19
	ds_read2_b32 v[14:15], v12 offset0:192 offset1:224
	s_waitcnt lgkmcnt(2)
	v_add_f32_e32 v6, v13, v6
	v_add_f32_e32 v6, v6, v7
	s_waitcnt lgkmcnt(1)
	v_add_f32_e32 v6, v6, v8
	v_add_f32_e32 v6, v6, v9
	s_waitcnt lgkmcnt(0)
	v_add_f32_e32 v6, v6, v14
	v_add_f32_e32 v8, v6, v15
	v_lshl_add_u32 v6, s35, 5, v0
	v_ashrrev_i32_e32 v7, 31, v6
	v_lshl_add_u64 v[6:7], v[6:7], 2, s[6:7]
	global_store_dword v[6:7], v8, off
	s_branch .LBB0_162
